# convpool unit: the 14 pool-window row loads issued together with the conv loads (addresses recomputed early), one latency per unit instead of two
# baseline (speedup 1.0000x reference)
.Lcp_i2:
	s_or_b64 exec, exec, s[0:1]
	v_lshlrev_b32_e32 v148, 2, v32
	global_load_dwordx4 v[144:147], v148, s[28:29] offset:1024
	global_load_dwordx4 v[46:49], v148, s[28:29] offset:1040
	global_load_dwordx4 v[50:53], v148, s[28:29]
	global_load_dwordx4 v[54:57], v148, s[28:29] offset:16
	global_load_dwordx4 v[58:61], v148, s[28:29] offset:2048
	global_load_dwordx4 v[62:65], v148, s[28:29] offset:2064
	v_lshrrev_b32_e32 v149, 6, v32
	v_lshlrev_b32_e64 v149, v149, 2
	v_lshrrev_b32_e32 v151, 1, v149
	v_add_u32_e32 v149, v30, v149
	v_sub_u32_e32 v150, v31, v151
	v_subrev_u32_e32 v149, s23, v149
	v_add_u32_e32 v150, s71, v150
	v_sub_u32_e32 v149, v149, v151
	v_add_u32_e32 v150, -1, v150
	v_add3_u32 v149, s71, v149, -1
	v_min_i32_e32 v151, s26, v149
	s_lshl_b32 s0, s23, 12
	s_add_u32 s0, s4, s0
	s_addc_u32 s1, s5, 0
	v_lshl_add_u64 v[152:153], s[0:1], 0, v[184:185]
	v_mov_b32_e32 v149, v150
	v_cmp_lt_i32_e32 vcc, -1, v150
	v_cmp_lt_i32_e64 s[0:1], v149, v151
	s_and_b64 s[0:1], vcc, s[0:1]
	v_cndmask_b32_e64 v154, v45, v149, s[0:1]
	v_ashrrev_i32_e32 v155, 31, v154
	v_lshlrev_b64 v[154:155], 12, v[154:155]
	v_lshl_add_u64 v[154:155], v[152:153], 0, v[154:155]
	global_load_dwordx4 v[156:159], v[154:155], off offset:3584
	v_add_u32_e32 v149, 1, v150
	v_cmp_lt_i32_e32 vcc, -2, v150
	v_cmp_lt_i32_e64 s[0:1], v149, v151
	s_and_b64 s[0:1], vcc, s[0:1]
	v_cndmask_b32_e64 v154, v45, v149, s[0:1]
	v_ashrrev_i32_e32 v155, 31, v154
	v_lshlrev_b64 v[154:155], 12, v[154:155]
	v_lshl_add_u64 v[154:155], v[152:153], 0, v[154:155]
	global_load_dwordx4 v[160:163], v[154:155], off offset:3584
	v_add_u32_e32 v149, 2, v150
	v_cmp_lt_i32_e32 vcc, -3, v150
	v_cmp_lt_i32_e64 s[0:1], v149, v151
	s_and_b64 s[0:1], vcc, s[0:1]
	v_cndmask_b32_e64 v154, v45, v149, s[0:1]
	v_ashrrev_i32_e32 v155, 31, v154
	v_lshlrev_b64 v[154:155], 12, v[154:155]
	v_lshl_add_u64 v[154:155], v[152:153], 0, v[154:155]
	global_load_dwordx4 v[164:167], v[154:155], off offset:3584
	v_add_u32_e32 v149, 3, v150
	v_cmp_lt_i32_e32 vcc, -4, v150
	v_cmp_lt_i32_e64 s[0:1], v149, v151
	s_and_b64 s[0:1], vcc, s[0:1]
	v_cndmask_b32_e64 v154, v45, v149, s[0:1]
	v_ashrrev_i32_e32 v155, 31, v154
	v_lshlrev_b64 v[154:155], 12, v[154:155]
	v_lshl_add_u64 v[154:155], v[152:153], 0, v[154:155]
	global_load_dwordx4 v[168:171], v[154:155], off offset:3584
	v_add_u32_e32 v149, 4, v150
	v_cmp_lt_i32_e32 vcc, -5, v150
	v_cmp_lt_i32_e64 s[0:1], v149, v151
	s_and_b64 s[0:1], vcc, s[0:1]
	v_cndmask_b32_e64 v154, v45, v149, s[0:1]
	v_ashrrev_i32_e32 v155, 31, v154
	v_lshlrev_b64 v[154:155], 12, v[154:155]
	v_lshl_add_u64 v[154:155], v[152:153], 0, v[154:155]
	global_load_dwordx4 v[172:175], v[154:155], off offset:3584
	v_add_u32_e32 v149, 5, v150
	v_cmp_lt_i32_e32 vcc, -6, v150
	v_cmp_lt_i32_e64 s[0:1], v149, v151
	s_and_b64 s[0:1], vcc, s[0:1]
	v_cndmask_b32_e64 v154, v45, v149, s[0:1]
	v_ashrrev_i32_e32 v155, 31, v154
	v_lshlrev_b64 v[154:155], 12, v[154:155]
	v_lshl_add_u64 v[154:155], v[152:153], 0, v[154:155]
	global_load_dwordx4 v[176:179], v[154:155], off offset:3584
	v_add_u32_e32 v149, 6, v150
	v_cmp_lt_i32_e32 vcc, -7, v150
	v_cmp_lt_i32_e64 s[0:1], v149, v151
	s_and_b64 s[0:1], vcc, s[0:1]
	v_cndmask_b32_e64 v154, v45, v149, s[0:1]
	v_ashrrev_i32_e32 v155, 31, v154
	v_lshlrev_b64 v[154:155], 12, v[154:155]
	v_lshl_add_u64 v[154:155], v[152:153], 0, v[154:155]
	global_load_dwordx4 v[180:183], v[154:155], off offset:3584
	v_add_u32_e32 v149, 7, v150
	v_cmp_lt_i32_e32 vcc, -8, v150
	v_cmp_lt_i32_e64 s[0:1], v149, v151
	s_and_b64 s[0:1], vcc, s[0:1]
	v_cndmask_b32_e64 v154, v45, v149, s[0:1]
	v_ashrrev_i32_e32 v155, 31, v154
	v_lshlrev_b64 v[154:155], 12, v[154:155]
	v_lshl_add_u64 v[154:155], v[152:153], 0, v[154:155]
	global_load_dwordx4 v[194:197], v[154:155], off offset:3584
	v_add_u32_e32 v149, 8, v150
	v_cmp_lt_i32_e32 vcc, -9, v150
	v_cmp_lt_i32_e64 s[0:1], v149, v151
	s_and_b64 s[0:1], vcc, s[0:1]
	v_cndmask_b32_e64 v154, v45, v149, s[0:1]
	v_ashrrev_i32_e32 v155, 31, v154
	v_lshlrev_b64 v[154:155], 12, v[154:155]
	v_lshl_add_u64 v[154:155], v[152:153], 0, v[154:155]
	global_load_dwordx4 v[198:201], v[154:155], off offset:3584
	v_add_u32_e32 v149, 9, v150
	v_cmp_lt_i32_e32 vcc, -10, v150
	v_cmp_lt_i32_e64 s[0:1], v149, v151
	s_and_b64 s[0:1], vcc, s[0:1]
	v_cndmask_b32_e64 v154, v45, v149, s[0:1]
	v_ashrrev_i32_e32 v155, 31, v154
	v_lshlrev_b64 v[154:155], 12, v[154:155]
	v_lshl_add_u64 v[154:155], v[152:153], 0, v[154:155]
	global_load_dwordx4 v[202:205], v[154:155], off offset:3584
	v_add_u32_e32 v149, 10, v150
	v_cmp_lt_i32_e32 vcc, -11, v150
	v_cmp_lt_i32_e64 s[0:1], v149, v151
	s_and_b64 s[0:1], vcc, s[0:1]
	v_cndmask_b32_e64 v154, v45, v149, s[0:1]
	v_ashrrev_i32_e32 v155, 31, v154
	v_lshlrev_b64 v[154:155], 12, v[154:155]
	v_lshl_add_u64 v[154:155], v[152:153], 0, v[154:155]
	global_load_dwordx4 v[206:209], v[154:155], off offset:3584
	v_add_u32_e32 v149, 11, v150
	v_cmp_lt_i32_e32 vcc, -12, v150
	v_cmp_lt_i32_e64 s[0:1], v149, v151
	s_and_b64 s[0:1], vcc, s[0:1]
	v_cndmask_b32_e64 v154, v45, v149, s[0:1]
	v_ashrrev_i32_e32 v155, 31, v154
	v_lshlrev_b64 v[154:155], 12, v[154:155]
	v_lshl_add_u64 v[154:155], v[152:153], 0, v[154:155]
	global_load_dwordx4 v[210:213], v[154:155], off offset:3584
	v_add_u32_e32 v149, 12, v150
	v_cmp_lt_i32_e32 vcc, -13, v150
	v_cmp_lt_i32_e64 s[0:1], v149, v151
	s_and_b64 s[0:1], vcc, s[0:1]
	v_cndmask_b32_e64 v154, v45, v149, s[0:1]
	v_ashrrev_i32_e32 v155, 31, v154
	v_lshlrev_b64 v[154:155], 12, v[154:155]
	v_lshl_add_u64 v[154:155], v[152:153], 0, v[154:155]
	global_load_dwordx4 v[214:217], v[154:155], off offset:3584
	v_add_u32_e32 v149, 13, v150
	v_cmp_lt_i32_e32 vcc, -14, v150
	v_cmp_lt_i32_e64 s[0:1], v149, v151
	s_and_b64 s[0:1], vcc, s[0:1]
	v_cndmask_b32_e64 v154, v45, v149, s[0:1]
	v_ashrrev_i32_e32 v155, 31, v154
	v_lshlrev_b64 v[154:155], 12, v[154:155]
	v_lshl_add_u64 v[154:155], v[152:153], 0, v[154:155]
	global_load_dwordx4 v[242:245], v[154:155], off offset:3584
	v_cmp_lt_i32_e32 vcc, 0, v45
	s_and_saveexec_b64 s[36:37], vcc
	s_cbranch_execz .Lcp_c1
	s_waitcnt vmcnt(20)
	v_lshlrev_b32_e32 v16, 16, v128
	v_and_b32_e32 v17, 0xffff0000, v128
	v_lshlrev_b32_e32 v12, 16, v129
	v_and_b32_e32 v13, 0xffff0000, v129
	v_lshlrev_b32_e32 v24, 16, v130
	v_and_b32_e32 v25, 0xffff0000, v130
	v_lshlrev_b32_e32 v26, 16, v131
	v_and_b32_e32 v27, 0xffff0000, v131
	v_lshlrev_b32_e32 v14, 16, v132
	v_and_b32_e32 v15, 0xffff0000, v132
	v_lshlrev_b32_e32 v20, 16, v133
	v_and_b32_e32 v21, 0xffff0000, v133
	v_lshlrev_b32_e32 v34, 16, v134
	v_and_b32_e32 v35, 0xffff0000, v134
	v_lshlrev_b32_e32 v22, 16, v135
	v_and_b32_e32 v23, 0xffff0000, v135
	v_pk_mul_f32 v[16:17], v[16:17], v[14:15]
	v_pk_mul_f32 v[20:21], v[12:13], v[20:21]
	v_pk_mul_f32 v[14:15], v[24:25], v[34:35]
	v_pk_mul_f32 v[12:13], v[26:27], v[22:23]
.Lcp_c1:
	s_or_b64 exec, exec, s[36:37]
	v_mov_b32_e32 v19, 0
	v_mov_b32_e32 v26, 0
	v_mov_b32_e32 v27, 0
	v_mov_b32_e32 v24, 0
	v_mov_b32_e32 v25, 0
	v_mov_b32_e32 v22, 0
	v_mov_b32_e32 v23, 0
	s_add_i32 s0, s26, -1
	v_cmp_gt_i32_e32 vcc, s0, v45
	s_and_saveexec_b64 s[0:1], vcc
	s_cbranch_execz .Lcp_c2
	s_waitcnt vmcnt(20)
	v_lshlrev_b32_e32 v18, 16, v136
	v_and_b32_e32 v19, 0xffff0000, v136
	v_lshlrev_b32_e32 v22, 16, v137
	v_and_b32_e32 v23, 0xffff0000, v137
	v_lshlrev_b32_e32 v34, 16, v138
	v_and_b32_e32 v35, 0xffff0000, v138
	v_lshlrev_b32_e32 v36, 16, v139
	v_and_b32_e32 v37, 0xffff0000, v139
	v_lshlrev_b32_e32 v24, 16, v140
	v_and_b32_e32 v25, 0xffff0000, v140
	v_lshlrev_b32_e32 v26, 16, v141
	v_and_b32_e32 v27, 0xffff0000, v141
	v_lshlrev_b32_e32 v38, 16, v142
	v_and_b32_e32 v39, 0xffff0000, v142
	v_lshlrev_b32_e32 v28, 16, v143
	v_and_b32_e32 v29, 0xffff0000, v143
	v_pk_mul_f32 v[18:19], v[18:19], v[24:25]
	v_pk_mul_f32 v[26:27], v[22:23], v[26:27]
	v_pk_mul_f32 v[24:25], v[34:35], v[38:39]
	v_pk_mul_f32 v[22:23], v[36:37], v[28:29]
.Lcp_c2:
	s_or_b64 exec, exec, s[0:1]
	v_lshrrev_b32_e32 v32, 6, v32
	s_waitcnt vmcnt(21)
	v_and_b32_e32 v39, 0xffff0000, v3
	s_waitcnt vmcnt(20)
	v_and_b32_e32 v44, 0xffff0000, v7
	v_lshlrev_b32_e64 v32, v32, 2
	v_mul_f32_e32 v39, v39, v44
	v_lshrrev_b32_e32 v44, 1, v32
	v_add_u32_e32 v30, v30, v32
	v_sub_u32_e32 v31, v31, v44
	v_subrev_u32_e32 v30, s23, v30
	v_add_u32_e32 v74, s71, v31
	v_sub_u32_e32 v30, v30, v44
	v_add_u32_e32 v75, -1, v74
	v_add3_u32 v30, s71, v30, -1
	v_min_i32_e32 v76, s26, v30
	v_max_i32_e32 v30, 0, v75
	v_sub_u32_e32 v30, v76, v30
	v_cvt_f32_i32_e32 v30, v30
	v_and_b32_e32 v68, 0xffff0000, v4
	v_lshlrev_b32_e32 v4, 16, v4
	v_and_b32_e32 v71, 0xffff0000, v0
	v_div_scale_f32 v31, s[0:1], v30, v30, 1.0
	v_rcp_f32_e32 v32, v31
	v_lshlrev_b32_e32 v0, 16, v0
	v_mul_f32_e32 v0, v0, v4
	v_div_scale_f32 v4, vcc, 1.0, v30, 1.0
	v_fma_f32 v44, -v31, v32, 1.0
	v_fmac_f32_e32 v32, v44, v32
	v_lshlrev_b32_e32 v7, 16, v7
	v_and_b32_e32 v66, 0xffff0000, v6
	v_lshlrev_b32_e32 v3, 16, v3
	v_and_b32_e32 v69, 0xffff0000, v2
	v_mul_f32_e32 v44, v4, v32
	v_mul_f32_e32 v3, v3, v7
	v_mul_f32_e32 v7, v69, v66
	v_fma_f32 v66, -v31, v44, v4
	v_fmac_f32_e32 v44, v66, v32
	v_lshlrev_b32_e32 v6, 16, v6
	v_and_b32_e32 v67, 0xffff0000, v5
	v_lshlrev_b32_e32 v5, 16, v5
	v_lshlrev_b32_e32 v2, 16, v2
	v_and_b32_e32 v70, 0xffff0000, v1
	v_lshlrev_b32_e32 v1, 16, v1
	v_fma_f32 v4, -v31, v44, v4
	v_mul_f32_e32 v2, v2, v6
	v_mul_f32_e32 v6, v70, v67
	v_mul_f32_e32 v1, v1, v5
	v_mul_f32_e32 v5, v71, v68
	v_div_fmas_f32 v4, v4, v32, v44
	v_div_fixup_f32 v44, v4, v30, 1.0
	s_lshl_b32 s0, s23, 12
	v_lshlrev_b32_e32 v28, 16, v8
	v_and_b32_e32 v8, 0xffff0000, v8
	v_lshlrev_b32_e32 v29, 16, v9
	v_and_b32_e32 v9, 0xffff0000, v9
	s_add_u32 s0, s4, s0
	s_addc_u32 s1, s5, 0
	v_lshlrev_b32_e32 v33, 16, v10
	v_and_b32_e32 v10, 0xffff0000, v10
	v_cmp_lt_i32_e32 vcc, -1, v75
	v_lshlrev_b32_e32 v38, 16, v11
	v_and_b32_e32 v11, 0xffff0000, v11
	v_readlane_b32 s4, v253, 16
	v_readlane_b32 s8, v253, 20
	v_readlane_b32 s9, v253, 21
	v_readlane_b32 s5, v253, 17
	s_nop 1
	s_waitcnt vmcnt(19)
	v_mul_f32_e32 v0, v0, v144
	v_mul_f32_e32 v4, v5, v145
	v_mul_f32_e32 v1, v1, v146
	v_mul_f32_e32 v5, v6, v147
	s_waitcnt vmcnt(17)
	v_fmac_f32_e32 v0, v16, v50
	v_fmac_f32_e32 v4, v17, v51
	v_fmac_f32_e32 v1, v20, v52
	v_fmac_f32_e32 v5, v21, v53
	v_mul_f32_e32 v2, v2, v46
	s_waitcnt vmcnt(15)
	v_fmac_f32_e32 v0, v18, v58
	v_fmac_f32_e32 v4, v19, v59
	v_fmac_f32_e32 v1, v26, v60
	v_fmac_f32_e32 v5, v27, v61
	v_mul_f32_e32 v6, v7, v47
	v_fmac_f32_e32 v2, v14, v54
	v_mul_f32_e32 v0, v0, v28
	v_mul_f32_e32 v4, v4, v8
	v_mul_f32_e32 v1, v1, v29
	v_mul_f32_e32 v5, v5, v9
	v_fmac_f32_e32 v6, v15, v55
	v_mul_f32_e32 v3, v3, v48
	v_mul_f32_e32 v7, v39, v49
	s_waitcnt vmcnt(14)
	v_fmac_f32_e32 v2, v24, v62
	v_fmac_f32_e32 v6, v25, v63
	v_fmac_f32_e32 v3, v12, v56
	v_fmac_f32_e32 v7, v13, v57
	v_cvt_pk_bf16_f32 v0, v0, v4
	v_cvt_pk_bf16_f32 v1, v1, v5
	v_lshl_add_u64 v[4:5], s[0:1], 0, v[184:185]
	v_cmp_gt_i32_e64 s[0:1], s26, v75
	v_mul_f32_e32 v2, v2, v33
	v_mul_f32_e32 v6, v6, v10
	v_fmac_f32_e32 v3, v22, v64
	v_fmac_f32_e32 v7, v23, v65
	s_and_b64 s[64:65], vcc, s[0:1]
	v_cmp_lt_i32_e32 vcc, -2, v75
	v_cmp_lt_i32_e64 s[0:1], v74, v76
	v_mul_f32_e32 v3, v3, v38
	v_mul_f32_e32 v7, v7, v11
	v_cvt_pk_bf16_f32 v2, v2, v6
	v_cndmask_b32_e64 v6, v45, v75, s[64:65]
	s_and_b64 s[62:63], vcc, s[0:1]
	v_cvt_pk_bf16_f32 v3, v3, v7
	v_ashrrev_i32_e32 v7, 31, v6
	v_cndmask_b32_e64 v8, v45, v74, s[62:63]
	v_lshlrev_b64 v[6:7], 12, v[6:7]
	v_ashrrev_i32_e32 v9, 31, v8
	v_lshl_add_u64 v[6:7], v[4:5], 0, v[6:7]
	v_lshlrev_b64 v[8:9], 12, v[8:9]
	v_lshl_add_u64 v[8:9], v[4:5], 0, v[8:9]
	v_add_u32_e32 v6, 1, v74
	v_cmp_lt_i32_e32 vcc, -3, v75
	v_cmp_lt_i32_e64 s[0:1], v6, v76
	v_add_u32_e32 v8, 2, v74
	s_and_b64 s[60:61], vcc, s[0:1]
	v_cmp_lt_i32_e32 vcc, -4, v75
	v_cmp_lt_i32_e64 s[0:1], v8, v76
	v_cndmask_b32_e64 v6, v45, v6, s[60:61]
	s_and_b64 s[58:59], vcc, s[0:1]
	v_ashrrev_i32_e32 v7, 31, v6
	v_cndmask_b32_e64 v8, v45, v8, s[58:59]
	v_lshlrev_b64 v[6:7], 12, v[6:7]
	v_ashrrev_i32_e32 v9, 31, v8
	v_lshl_add_u64 v[6:7], v[4:5], 0, v[6:7]
	v_lshlrev_b64 v[8:9], 12, v[8:9]
	v_lshl_add_u64 v[8:9], v[4:5], 0, v[8:9]
	v_add_u32_e32 v6, 3, v74
	v_cmp_lt_i32_e32 vcc, -5, v75
	v_cmp_lt_i32_e64 s[0:1], v6, v76
	v_add_u32_e32 v8, 4, v74
	s_and_b64 s[0:1], vcc, s[0:1]
	v_cmp_lt_i32_e32 vcc, -6, v75
	v_cmp_lt_i32_e64 s[36:37], v8, v76
	v_cndmask_b32_e64 v6, v45, v6, s[0:1]
	s_and_b64 s[54:55], vcc, s[36:37]
	v_ashrrev_i32_e32 v7, 31, v6
	v_cndmask_b32_e64 v8, v45, v8, s[54:55]
	v_lshlrev_b64 v[6:7], 12, v[6:7]
	v_ashrrev_i32_e32 v9, 31, v8
	v_lshl_add_u64 v[6:7], v[4:5], 0, v[6:7]
	v_lshlrev_b64 v[8:9], 12, v[8:9]
	v_lshl_add_u64 v[8:9], v[4:5], 0, v[8:9]
	v_add_u32_e32 v6, 5, v74
	v_cmp_lt_i32_e32 vcc, -7, v75
	v_cmp_lt_i32_e64 s[36:37], v6, v76
	v_add_u32_e32 v8, 6, v74
	s_and_b64 s[52:53], vcc, s[36:37]
	v_cmp_lt_i32_e32 vcc, -8, v75
	v_cmp_lt_i32_e64 s[36:37], v8, v76
	v_cndmask_b32_e64 v6, v45, v6, s[52:53]
	s_and_b64 s[50:51], vcc, s[36:37]
	v_ashrrev_i32_e32 v7, 31, v6
	v_cndmask_b32_e64 v8, v45, v8, s[50:51]
	v_lshlrev_b64 v[6:7], 12, v[6:7]
	v_ashrrev_i32_e32 v9, 31, v8
	v_lshl_add_u64 v[6:7], v[4:5], 0, v[6:7]
	v_lshlrev_b64 v[8:9], 12, v[8:9]
	v_lshl_add_u64 v[8:9], v[4:5], 0, v[8:9]
	v_add_u32_e32 v6, 7, v74
	v_cmp_lt_i32_e32 vcc, -9, v75
	v_cmp_lt_i32_e64 s[36:37], v6, v76
	v_add_u32_e32 v8, 8, v74
	s_and_b64 s[48:49], vcc, s[36:37]
	v_cmp_lt_i32_e32 vcc, -10, v75
	v_cmp_lt_i32_e64 s[36:37], v8, v76
	v_cndmask_b32_e64 v6, v45, v6, s[48:49]
	s_and_b64 s[46:47], vcc, s[36:37]
	v_ashrrev_i32_e32 v7, 31, v6
	v_cndmask_b32_e64 v8, v45, v8, s[46:47]
	v_lshlrev_b64 v[6:7], 12, v[6:7]
	v_ashrrev_i32_e32 v9, 31, v8
	v_lshl_add_u64 v[6:7], v[4:5], 0, v[6:7]
	v_lshlrev_b64 v[8:9], 12, v[8:9]
	v_lshl_add_u64 v[8:9], v[4:5], 0, v[8:9]
	v_add_u32_e32 v6, 9, v74
	v_cmp_lt_i32_e32 vcc, -11, v75
	v_cmp_lt_i32_e64 s[36:37], v6, v76
	v_add_u32_e32 v8, 10, v74
	s_and_b64 s[44:45], vcc, s[36:37]
	v_cmp_lt_i32_e32 vcc, -12, v75
	v_cmp_lt_i32_e64 s[36:37], v8, v76
	v_cndmask_b32_e64 v6, v45, v6, s[44:45]
	s_and_b64 s[42:43], vcc, s[36:37]
	v_ashrrev_i32_e32 v7, 31, v6
	v_cndmask_b32_e64 v8, v45, v8, s[42:43]
	v_lshlrev_b64 v[6:7], 12, v[6:7]
	v_ashrrev_i32_e32 v9, 31, v8
	v_lshl_add_u64 v[6:7], v[4:5], 0, v[6:7]
	v_lshlrev_b64 v[8:9], 12, v[8:9]
	v_lshl_add_u64 v[8:9], v[4:5], 0, v[8:9]
	v_add_u32_e32 v6, 11, v74
	v_cmp_lt_i32_e32 vcc, -13, v75
	v_cmp_lt_i32_e64 s[36:37], v6, v76
	v_add_u32_e32 v8, 12, v74
	s_and_b64 s[40:41], vcc, s[36:37]
	v_cmp_lt_i32_e32 vcc, -14, v75
	v_cmp_lt_i32_e64 s[36:37], v8, v76
	v_cndmask_b32_e64 v6, v45, v6, s[40:41]
	s_and_b64 s[38:39], vcc, s[36:37]
	v_ashrrev_i32_e32 v7, 31, v6
	v_cndmask_b32_e64 v8, v45, v8, s[38:39]
	v_lshlrev_b64 v[6:7], 12, v[6:7]
	v_ashrrev_i32_e32 v9, 31, v8
	v_lshl_add_u64 v[6:7], v[4:5], 0, v[6:7]
	v_lshlrev_b64 v[8:9], 12, v[8:9]
	v_lshl_add_u64 v[8:9], v[4:5], 0, v[8:9]
	v_add_u32_e32 v6, 13, v74
	v_cmp_lt_i32_e32 vcc, -15, v75
	v_cmp_lt_i32_e64 s[36:37], v6, v76
	v_add_u32_e32 v8, 14, v74
	s_and_b64 s[36:37], vcc, s[36:37]
	v_cmp_lt_i32_e32 vcc, -16, v75
	v_cmp_lt_i32_e64 s[68:69], v8, v76
	s_and_b64 vcc, vcc, s[68:69]
	s_waitcnt vmcnt(13)
	v_lshlrev_b32_e32 v76, 16, v159
	v_and_b32_e32 v49, 0xffff0000, v159
	v_cndmask_b32_e64 v6, v45, v6, s[36:37]
	v_cndmask_b32_e32 v8, v45, v8, vcc
	v_lshlrev_b32_e32 v45, 16, v156
	v_and_b32_e32 v46, 0xffff0000, v156
	v_add_f32_e32 v49, 0, v49
	s_waitcnt vmcnt(12)
	v_lshlrev_b32_e32 v80, 16, v163
	v_and_b32_e32 v53, 0xffff0000, v163
	v_lshlrev_b32_e32 v74, 16, v157
	v_add_f32_e32 v45, 0, v45
	v_add_f32_e32 v46, 0, v46
	v_cndmask_b32_e64 v49, 0, v49, s[64:65]
	v_lshlrev_b32_e32 v77, 16, v160
	v_and_b32_e32 v50, 0xffff0000, v160
	v_cndmask_b32_e64 v53, 0, v53, s[62:63]
	v_and_b32_e32 v47, 0xffff0000, v157
	v_cndmask_b32_e64 v45, 0, v45, s[64:65]
	v_cndmask_b32_e64 v46, 0, v46, s[64:65]
	v_add_f32_e32 v74, 0, v74
	v_lshlrev_b32_e32 v78, 16, v161
	v_cndmask_b32_e64 v77, 0, v77, s[62:63]
	v_cndmask_b32_e64 v50, 0, v50, s[62:63]
	v_add_f32_e32 v49, v49, v53
	s_waitcnt vmcnt(11)
	v_lshlrev_b32_e32 v53, 16, v164
	v_lshlrev_b32_e32 v75, 16, v158
	v_cndmask_b32_e64 v74, 0, v74, s[64:65]
	v_add_f32_e32 v47, 0, v47
	v_and_b32_e32 v51, 0xffff0000, v161
	v_add_f32_e32 v45, v45, v77
	v_add_f32_e32 v46, v46, v50
	v_cndmask_b32_e64 v50, 0, v78, s[62:63]
	v_and_b32_e32 v54, 0xffff0000, v164
	v_cndmask_b32_e64 v53, 0, v53, s[60:61]
	v_and_b32_e32 v48, 0xffff0000, v158
	v_cndmask_b32_e64 v47, 0, v47, s[64:65]
	v_add_f32_e32 v75, 0, v75
	v_lshlrev_b32_e32 v79, 16, v162
	v_add_f32_e32 v50, v74, v50
	v_cndmask_b32_e64 v51, 0, v51, s[62:63]
	v_lshlrev_b32_e32 v74, 16, v165
	v_add_f32_e32 v45, v45, v53
	v_cndmask_b32_e64 v53, 0, v54, s[60:61]
	v_cndmask_b32_e64 v75, 0, v75, s[64:65]
	v_add_f32_e32 v48, 0, v48
	v_and_b32_e32 v52, 0xffff0000, v162
	v_add_f32_e32 v47, v47, v51
	v_cndmask_b32_e64 v51, 0, v79, s[62:63]
	v_and_b32_e32 v55, 0xffff0000, v165
	v_add_f32_e32 v46, v46, v53
	v_cndmask_b32_e64 v53, 0, v74, s[60:61]
	v_cndmask_b32_e64 v48, 0, v48, s[64:65]
	v_add_f32_e32 v76, 0, v76
	v_add_f32_e32 v51, v75, v51
	v_cndmask_b32_e64 v52, 0, v52, s[62:63]
	v_lshlrev_b32_e32 v75, 16, v166
	v_add_f32_e32 v50, v50, v53
	v_cndmask_b32_e64 v53, 0, v55, s[60:61]
	v_cndmask_b32_e64 v76, 0, v76, s[64:65]
	v_add_f32_e32 v48, v48, v52
	v_cndmask_b32_e64 v52, 0, v80, s[62:63]
	v_and_b32_e32 v56, 0xffff0000, v166
	v_add_f32_e32 v47, v47, v53
	v_cndmask_b32_e64 v53, 0, v75, s[60:61]
	v_add_f32_e32 v52, v76, v52
	v_lshlrev_b32_e32 v76, 16, v167
	v_add_f32_e32 v51, v51, v53
	v_cndmask_b32_e64 v53, 0, v56, s[60:61]
	v_and_b32_e32 v57, 0xffff0000, v167
	v_add_f32_e32 v48, v48, v53
	v_cndmask_b32_e64 v53, 0, v76, s[60:61]
	v_add_f32_e32 v52, v52, v53
	v_cndmask_b32_e64 v53, 0, v57, s[60:61]
	v_add_f32_e32 v49, v49, v53
	s_waitcnt vmcnt(10)
	v_lshlrev_b32_e32 v53, 16, v168
	v_and_b32_e32 v54, 0xffff0000, v168
	v_cndmask_b32_e64 v53, 0, v53, s[58:59]
	v_lshlrev_b32_e32 v55, 16, v169
	v_add_f32_e32 v45, v45, v53
	v_cndmask_b32_e64 v53, 0, v54, s[58:59]
	v_and_b32_e32 v56, 0xffff0000, v169
	v_add_f32_e32 v46, v46, v53
	v_cndmask_b32_e64 v53, 0, v55, s[58:59]
	v_lshlrev_b32_e32 v57, 16, v170
	v_add_f32_e32 v50, v50, v53
	v_cndmask_b32_e64 v53, 0, v56, s[58:59]
	v_and_b32_e32 v58, 0xffff0000, v170
	v_add_f32_e32 v47, v47, v53
	v_cndmask_b32_e64 v53, 0, v57, s[58:59]
	v_lshlrev_b32_e32 v59, 16, v171
	v_add_f32_e32 v51, v51, v53
	v_cndmask_b32_e64 v53, 0, v58, s[58:59]
	v_and_b32_e32 v60, 0xffff0000, v171
	v_add_f32_e32 v48, v48, v53
	v_cndmask_b32_e64 v53, 0, v59, s[58:59]
	v_add_f32_e32 v52, v52, v53
	v_cndmask_b32_e64 v53, 0, v60, s[58:59]
	v_add_f32_e32 v49, v49, v53
	s_waitcnt vmcnt(9)
	v_lshlrev_b32_e32 v53, 16, v172
	v_and_b32_e32 v54, 0xffff0000, v172
	v_cndmask_b32_e64 v53, 0, v53, s[0:1]
	v_lshlrev_b32_e32 v55, 16, v173
	v_add_f32_e32 v45, v45, v53
	v_cndmask_b32_e64 v53, 0, v54, s[0:1]
	v_and_b32_e32 v56, 0xffff0000, v173
	v_add_f32_e32 v46, v46, v53
	v_cndmask_b32_e64 v53, 0, v55, s[0:1]
	v_lshlrev_b32_e32 v57, 16, v174
	v_add_f32_e32 v50, v50, v53
	v_cndmask_b32_e64 v53, 0, v56, s[0:1]
	v_and_b32_e32 v58, 0xffff0000, v174
	v_add_f32_e32 v47, v47, v53
	v_cndmask_b32_e64 v53, 0, v57, s[0:1]
	v_lshlrev_b32_e32 v59, 16, v175
	v_add_f32_e32 v51, v51, v53
	v_cndmask_b32_e64 v53, 0, v58, s[0:1]
	v_and_b32_e32 v60, 0xffff0000, v175
	v_add_f32_e32 v48, v48, v53
	v_cndmask_b32_e64 v53, 0, v59, s[0:1]
	v_add_f32_e32 v52, v52, v53
	v_cndmask_b32_e64 v53, 0, v60, s[0:1]
	v_add_f32_e32 v49, v49, v53
	s_waitcnt vmcnt(8)
	v_lshlrev_b32_e32 v53, 16, v176
	v_and_b32_e32 v54, 0xffff0000, v176
	v_cndmask_b32_e64 v53, 0, v53, s[54:55]
	v_lshlrev_b32_e32 v55, 16, v177
	v_add_f32_e32 v45, v45, v53
	v_cndmask_b32_e64 v53, 0, v54, s[54:55]
	v_and_b32_e32 v56, 0xffff0000, v177
	v_add_f32_e32 v46, v46, v53
	v_cndmask_b32_e64 v53, 0, v55, s[54:55]
	v_lshlrev_b32_e32 v57, 16, v178
	v_add_f32_e32 v50, v50, v53
	v_cndmask_b32_e64 v53, 0, v56, s[54:55]
	v_and_b32_e32 v58, 0xffff0000, v178
	v_add_f32_e32 v47, v47, v53
	v_cndmask_b32_e64 v53, 0, v57, s[54:55]
	v_lshlrev_b32_e32 v59, 16, v179
	v_add_f32_e32 v51, v51, v53
	v_cndmask_b32_e64 v53, 0, v58, s[54:55]
	v_and_b32_e32 v60, 0xffff0000, v179
	v_add_f32_e32 v48, v48, v53
	v_cndmask_b32_e64 v53, 0, v59, s[54:55]
	v_add_f32_e32 v52, v52, v53
	v_cndmask_b32_e64 v53, 0, v60, s[54:55]
	v_add_f32_e32 v49, v49, v53
	s_waitcnt vmcnt(7)
	v_lshlrev_b32_e32 v53, 16, v180
	v_and_b32_e32 v54, 0xffff0000, v180
	v_cndmask_b32_e64 v53, 0, v53, s[52:53]
	v_lshlrev_b32_e32 v55, 16, v181
	v_add_f32_e32 v45, v45, v53
	v_cndmask_b32_e64 v53, 0, v54, s[52:53]
	v_and_b32_e32 v56, 0xffff0000, v181
	v_add_f32_e32 v46, v46, v53
	v_cndmask_b32_e64 v53, 0, v55, s[52:53]
	v_lshlrev_b32_e32 v57, 16, v182
	v_add_f32_e32 v50, v50, v53
	v_cndmask_b32_e64 v53, 0, v56, s[52:53]
	v_and_b32_e32 v58, 0xffff0000, v182
	v_add_f32_e32 v47, v47, v53
	v_cndmask_b32_e64 v53, 0, v57, s[52:53]
	v_lshlrev_b32_e32 v59, 16, v183
	v_add_f32_e32 v51, v51, v53
	v_cndmask_b32_e64 v53, 0, v58, s[52:53]
	v_and_b32_e32 v60, 0xffff0000, v183
	v_add_f32_e32 v48, v48, v53
	v_cndmask_b32_e64 v53, 0, v59, s[52:53]
	v_add_f32_e32 v52, v52, v53
	v_cndmask_b32_e64 v53, 0, v60, s[52:53]
	v_add_f32_e32 v49, v49, v53
	s_waitcnt vmcnt(6)
	v_lshlrev_b32_e32 v53, 16, v194
	v_and_b32_e32 v36, 0xffff0000, v194
	v_lshlrev_b32_e32 v56, 16, v197
	v_and_b32_e32 v39, 0xffff0000, v197
	v_lshlrev_b32_e32 v54, 16, v195
	v_and_b32_e32 v37, 0xffff0000, v195
	v_cndmask_b32_e64 v36, 0, v36, s[50:51]
	v_cndmask_b32_e64 v39, 0, v39, s[50:51]
	v_lshlrev_b32_e32 v55, 16, v196
	v_and_b32_e32 v38, 0xffff0000, v196
	v_add_f32_e32 v36, v46, v36
	v_cndmask_b32_e64 v46, 0, v54, s[50:51]
	v_cndmask_b32_e64 v37, 0, v37, s[50:51]
	v_add_f32_e32 v39, v49, v39
	s_waitcnt vmcnt(5)
	v_lshlrev_b32_e32 v49, 16, v198
	v_and_b32_e32 v32, 0xffff0000, v198
	v_add_f32_e32 v46, v50, v46
	v_add_f32_e32 v37, v47, v37
	v_cndmask_b32_e64 v47, 0, v55, s[50:51]
	v_cndmask_b32_e64 v38, 0, v38, s[50:51]
	v_lshlrev_b32_e32 v50, 16, v199
	v_and_b32_e32 v33, 0xffff0000, v199
	v_cndmask_b32_e64 v32, 0, v32, s[48:49]
	v_add_f32_e32 v47, v51, v47
	v_add_f32_e32 v38, v48, v38
	v_cndmask_b32_e64 v48, 0, v56, s[50:51]
	v_lshlrev_b32_e32 v51, 16, v200
	v_and_b32_e32 v34, 0xffff0000, v200
	v_add_f32_e32 v32, v36, v32
	v_cndmask_b32_e64 v36, 0, v50, s[48:49]
	v_cndmask_b32_e64 v33, 0, v33, s[48:49]
	v_add_f32_e32 v48, v52, v48
	v_lshlrev_b32_e32 v52, 16, v201
	v_and_b32_e32 v35, 0xffff0000, v201
	v_add_f32_e32 v36, v46, v36
	v_add_f32_e32 v33, v37, v33
	v_cndmask_b32_e64 v37, 0, v51, s[48:49]
	v_cndmask_b32_e64 v34, 0, v34, s[48:49]
	s_waitcnt vmcnt(4)
	v_lshlrev_b32_e32 v46, 16, v203
	v_and_b32_e32 v29, 0xffff0000, v203
	v_add_f32_e32 v37, v47, v37
	v_add_f32_e32 v34, v38, v34
	v_cndmask_b32_e64 v38, 0, v52, s[48:49]
	v_cndmask_b32_e64 v35, 0, v35, s[48:49]
	v_lshlrev_b32_e32 v47, 16, v204
	v_and_b32_e32 v30, 0xffff0000, v204
	v_cndmask_b32_e64 v29, 0, v29, s[46:47]
	v_add_f32_e32 v38, v48, v38
	v_add_f32_e32 v35, v39, v35
	v_lshlrev_b32_e32 v39, 16, v202
	v_and_b32_e32 v28, 0xffff0000, v202
	v_lshlrev_b32_e32 v48, 16, v205
	v_and_b32_e32 v31, 0xffff0000, v205
	v_add_f32_e32 v29, v33, v29
	v_cndmask_b32_e64 v33, 0, v47, s[46:47]
	v_cndmask_b32_e64 v30, 0, v30, s[46:47]
	v_cndmask_b32_e64 v28, 0, v28, s[46:47]
	v_add_f32_e32 v33, v37, v33
	v_add_f32_e32 v30, v34, v30
	v_cndmask_b32_e64 v34, 0, v48, s[46:47]
	v_cndmask_b32_e64 v31, 0, v31, s[46:47]
	s_waitcnt vmcnt(3)
	v_lshlrev_b32_e32 v37, 16, v208
	v_and_b32_e32 v26, 0xffff0000, v208
	v_ashrrev_i32_e32 v7, 31, v6
	v_ashrrev_i32_e32 v9, 31, v8
	v_add_f32_e32 v28, v32, v28
	v_cndmask_b32_e64 v32, 0, v46, s[46:47]
	v_add_f32_e32 v34, v38, v34
	v_add_f32_e32 v31, v35, v31
	v_lshlrev_b32_e32 v35, 16, v206
	v_and_b32_e32 v24, 0xffff0000, v206
	v_lshlrev_b32_e32 v38, 16, v209
	v_and_b32_e32 v27, 0xffff0000, v209
	v_cndmask_b32_e64 v26, 0, v26, s[44:45]
	v_lshlrev_b64 v[6:7], 12, v[6:7]
	v_lshlrev_b64 v[8:9], 12, v[8:9]
	v_add_f32_e32 v32, v36, v32
	v_lshlrev_b32_e32 v36, 16, v207
	v_and_b32_e32 v25, 0xffff0000, v207
	v_cndmask_b32_e64 v24, 0, v24, s[44:45]
	v_add_f32_e32 v26, v30, v26
	v_cndmask_b32_e64 v30, 0, v38, s[44:45]
	v_cndmask_b32_e64 v27, 0, v27, s[44:45]
	v_lshl_add_u64 v[6:7], v[4:5], 0, v[6:7]
	v_lshl_add_u64 v[4:5], v[4:5], 0, v[8:9]
	v_cndmask_b32_e64 v53, 0, v53, s[50:51]
	v_add_f32_e32 v24, v28, v24
	v_cndmask_b32_e64 v28, 0, v36, s[44:45]
	v_cndmask_b32_e64 v25, 0, v25, s[44:45]
	v_add_f32_e32 v30, v34, v30
	v_add_f32_e32 v27, v31, v27
	s_waitcnt vmcnt(2)
	v_lshlrev_b32_e32 v31, 16, v210
	v_and_b32_e32 v20, 0xffff0000, v210
	v_lshlrev_b32_e32 v34, 16, v213
	v_and_b32_e32 v23, 0xffff0000, v213
	global_load_dwordx4 v[8:11], v[6:7], off offset:3584
	s_nop 0
	global_load_dwordx4 v[4:7], v[4:5], off offset:3584
	v_add_f32_e32 v45, v45, v53
	v_cndmask_b32_e64 v49, 0, v49, s[48:49]
	v_add_f32_e32 v28, v32, v28
	v_add_f32_e32 v25, v29, v25
	v_cndmask_b32_e64 v29, 0, v37, s[44:45]
	v_lshlrev_b32_e32 v32, 16, v211
	v_cndmask_b32_e64 v20, 0, v20, s[42:43]
	v_cndmask_b32_e64 v23, 0, v23, s[42:43]
	v_add_f32_e32 v45, v45, v49
	v_cndmask_b32_e64 v39, 0, v39, s[46:47]
	v_add_f32_e32 v29, v33, v29
	v_and_b32_e32 v21, 0xffff0000, v211
	v_lshlrev_b32_e32 v33, 16, v212
	v_and_b32_e32 v22, 0xffff0000, v212
	v_add_f32_e32 v20, v24, v20
	v_cndmask_b32_e64 v24, 0, v32, s[42:43]
	v_add_f32_e32 v23, v27, v23
	s_waitcnt vmcnt(3)
	v_lshlrev_b32_e32 v27, 16, v214
	v_and_b32_e32 v16, 0xffff0000, v214
	v_add_f32_e32 v39, v45, v39
	v_cndmask_b32_e64 v35, 0, v35, s[44:45]
	v_add_f32_e32 v24, v28, v24
	v_cndmask_b32_e64 v21, 0, v21, s[42:43]
	v_cndmask_b32_e64 v22, 0, v22, s[42:43]
	v_lshlrev_b32_e32 v28, 16, v215
	v_cndmask_b32_e64 v16, 0, v16, s[40:41]
	v_add_f32_e32 v35, v39, v35
	v_cndmask_b32_e64 v31, 0, v31, s[42:43]
	v_add_f32_e32 v21, v25, v21
	v_cndmask_b32_e64 v25, 0, v33, s[42:43]
	v_add_f32_e32 v22, v26, v22
	v_cndmask_b32_e64 v26, 0, v34, s[42:43]
	v_and_b32_e32 v17, 0xffff0000, v215
	v_add_f32_e32 v20, v20, v16
	v_cndmask_b32_e64 v16, 0, v28, s[40:41]
	v_add_f32_e32 v31, v35, v31
	v_add_f32_e32 v25, v29, v25
	v_add_f32_e32 v26, v30, v26
	v_lshlrev_b32_e32 v29, 16, v216
	v_and_b32_e32 v30, 0xffff0000, v216
	v_cndmask_b32_e64 v18, 0, v27, s[40:41]
	v_add_f32_e32 v24, v24, v16
	v_cndmask_b32_e64 v16, 0, v17, s[40:41]
	v_lshlrev_b32_e32 v32, 16, v217
	v_and_b32_e32 v33, 0xffff0000, v217
	v_add_f32_e32 v27, v31, v18
	v_add_f32_e32 v21, v21, v16
	global_load_dwordx4 v[16:19], v[42:43], off offset:3584
	v_cndmask_b32_e64 v28, 0, v29, s[40:41]
	v_add_f32_e32 v25, v25, v28
	v_cndmask_b32_e64 v28, 0, v30, s[40:41]
	v_add_f32_e32 v22, v22, v28
	v_cndmask_b32_e64 v28, 0, v32, s[40:41]
	v_add_f32_e32 v26, v26, v28
	v_cndmask_b32_e64 v28, 0, v33, s[40:41]
	v_add_f32_e32 v23, v23, v28
	s_waitcnt vmcnt(3)
	v_lshlrev_b32_e32 v28, 16, v242
	v_and_b32_e32 v12, 0xffff0000, v242
	v_lshlrev_b32_e32 v29, 16, v243
	v_and_b32_e32 v13, 0xffff0000, v243
	v_lshlrev_b32_e32 v30, 16, v244
	v_and_b32_e32 v14, 0xffff0000, v244
	v_lshlrev_b32_e32 v31, 16, v245
	v_and_b32_e32 v15, 0xffff0000, v245
	v_cndmask_b32_e64 v12, 0, v12, s[38:39]
	v_add_f32_e32 v12, v20, v12
	v_cndmask_b32_e64 v20, 0, v29, s[38:39]
	v_cndmask_b32_e64 v13, 0, v13, s[38:39]
	v_cndmask_b32_e64 v14, 0, v14, s[38:39]
	v_cndmask_b32_e64 v15, 0, v15, s[38:39]
	v_add_f32_e32 v20, v24, v20
	v_add_f32_e32 v13, v21, v13
	v_cndmask_b32_e64 v21, 0, v30, s[38:39]
	v_add_f32_e32 v14, v22, v14
	v_cndmask_b32_e64 v22, 0, v31, s[38:39]
	v_add_f32_e32 v15, v23, v15
	v_add_f32_e32 v21, v25, v21
	v_add_f32_e32 v22, v26, v22
	s_waitcnt vmcnt(2)
	v_lshlrev_b32_e32 v23, 16, v8
	v_and_b32_e32 v8, 0xffff0000, v8
	v_lshlrev_b32_e32 v24, 16, v9
	v_and_b32_e32 v9, 0xffff0000, v9
	v_lshlrev_b32_e32 v25, 16, v10
	v_and_b32_e32 v10, 0xffff0000, v10
	v_lshlrev_b32_e32 v26, 16, v11
	v_and_b32_e32 v11, 0xffff0000, v11
	v_cndmask_b32_e64 v8, 0, v8, s[36:37]
	v_cndmask_b32_e64 v9, 0, v9, s[36:37]
	v_add_f32_e32 v8, v12, v8
	v_cndmask_b32_e64 v12, 0, v24, s[36:37]
	v_add_f32_e32 v9, v13, v9
	v_cndmask_b32_e64 v13, 0, v25, s[36:37]
	v_cndmask_b32_e64 v10, 0, v10, s[36:37]
	v_cndmask_b32_e64 v11, 0, v11, s[36:37]
	v_add_f32_e32 v12, v20, v12
	v_add_f32_e32 v13, v21, v13
	v_add_f32_e32 v10, v14, v10
	v_cndmask_b32_e64 v14, 0, v26, s[36:37]
	v_add_f32_e32 v11, v15, v11
	s_waitcnt vmcnt(1)
	v_lshlrev_b32_e32 v15, 16, v4
	v_and_b32_e32 v4, 0xffff0000, v4
	v_lshlrev_b32_e32 v20, 16, v5
	v_and_b32_e32 v5, 0xffff0000, v5
	v_lshlrev_b32_e32 v21, 16, v6
	v_and_b32_e32 v6, 0xffff0000, v6
	v_add_f32_e32 v14, v22, v14
	v_lshlrev_b32_e32 v22, 16, v7
	v_cndmask_b32_e32 v4, 0, v4, vcc
	v_cndmask_b32_e32 v5, 0, v5, vcc
	v_cndmask_b32_e32 v6, 0, v6, vcc
	v_add_f32_e32 v4, v8, v4
	v_cndmask_b32_e32 v8, 0, v20, vcc
	v_add_f32_e32 v5, v9, v5
	v_cndmask_b32_e32 v9, 0, v21, vcc
	v_add_f32_e32 v6, v10, v6
	v_cndmask_b32_e32 v10, 0, v22, vcc
	v_cndmask_b32_e64 v28, 0, v28, s[38:39]
	v_add_f32_e32 v8, v12, v8
	v_add_f32_e32 v9, v13, v9
	v_add_f32_e32 v10, v14, v10
	v_add_f32_e32 v27, v27, v28
	v_cndmask_b32_e64 v23, 0, v23, s[36:37]
	v_and_b32_e32 v7, 0xffff0000, v7
	v_add_f32_e32 v23, v27, v23
	v_cndmask_b32_e32 v15, 0, v15, vcc
	v_cndmask_b32_e32 v7, 0, v7, vcc
	v_add_f32_e32 v15, v23, v15
	s_waitcnt vmcnt(0)
	v_and_b32_e32 v12, 0xffff0000, v16
	v_lshlrev_b32_e32 v13, 16, v17
	v_and_b32_e32 v14, 0xffff0000, v17
	v_fma_f32 v12, v44, v4, -v12
	v_fma_f32 v8, v44, v8, -v13
	v_fma_f32 v13, v44, v5, -v14
	v_lshlrev_b64 v[4:5], 11, v[40:41]
	v_lshl_add_u64 v[4:5], s[8:9], 0, v[4:5]
	v_add_f32_e32 v7, v11, v7
	v_lshlrev_b32_e32 v11, 16, v16
	v_lshlrev_b32_e32 v16, 16, v18
	v_and_b32_e32 v17, 0xffff0000, v18
	v_lshlrev_b32_e32 v18, 16, v19
	v_and_b32_e32 v19, 0xffff0000, v19
	v_lshl_add_u64 v[4:5], v[4:5], 0, v[184:185]
	s_mov_b64 s[0:1], 0
	s_nop 1
	v_fma_f32 v11, v44, v15, -v11
	v_fma_f32 v9, v44, v9, -v16
	v_fma_f32 v6, v44, v6, -v17
	v_fma_f32 v10, v44, v10, -v18
	v_fma_f32 v7, v44, v7, -v19
	global_store_dwordx4 v[4:5], v[0:3], off offset:512
	s_nop 1
	v_cvt_pk_bf16_f32 v0, v11, v12
	v_cvt_pk_bf16_f32 v1, v8, v13
	v_cvt_pk_bf16_f32 v2, v9, v6
	v_cvt_pk_bf16_f32 v3, v10, v7
	global_store_dwordx4 v[4:5], v[0:3], off offset:1536
